# phase 1.5 loads issued together, later code kept at the same byte offsets as the previous best (matched placement)
# speedup vs baseline: 1.0103x; 1.0040x over previous
; #define LAS __attribute__((address_space(3)))
; __device__ __forceinline__ unsigned xb_ld(unsigned* p)              { return __hip_atomic_load(p, __ATOMIC_RELAXED, __HIP_MEMORY_SCOPE_AGENT); }
; __device__ __forceinline__ unsigned xb_xcc_id() { return (unsigned)__builtin_amdgcn_s_getreg((3 << 11) | 20) & 0xFu; }
; __device__ __forceinline__ void xcd_barrier_complete(unsigned* bar, unsigned x, unsigned& nloc, unsigned& nx) {
;     const unsigned G = gridDim.x * gridDim.y * gridDim.z;
;     unsigned sum, cnt, mine, sp = 0u;
;     for (;;) {
;         sum = 0u; cnt = 0u; mine = 0u;
; #pragma unroll
;         for (unsigned j = 0; j < 16; ++j) { const unsigned c = xb_ld(&bar[XB_XCNT(j)]); sum += c; cnt += (c > 0u) ? 1u : 0u; mine = (j == x) ? c : mine; }
; __device__ __forceinline__ void xcd_barrier(unsigned* bar, volatile LAS unsigned* st) {
;     asm volatile("s_waitcnt vmcnt(0)" ::: "memory");
;     __syncthreads();
;     if (threadIdx.x == 0) {
;         const unsigned x = xb_xcc_id();
;         __builtin_amdgcn_s_waitcnt(0);
;         unsigned nloc = st[0], nx = st[1];
;         if (nloc == 0u) { xcd_barrier_complete(bar, x, nloc, nx); st[0] = nloc; st[1] = nx; }
.LBB0_308:
	s_nop 0
	s_nop 0
	s_nop 0
	s_nop 0
	s_nop 0
	s_nop 0
	s_nop 0
	s_nop 0
	s_load_dwordx2 s[8:9], s[82:83], 0x78
	s_waitcnt lgkmcnt(0)
	s_waitcnt vmcnt(0)
	s_waitcnt lgkmcnt(0)
	s_barrier
	s_mov_b64 s[6:7], exec
	v_readlane_b32 s0, v255, 4
	v_readlane_b32 s1, v255, 5
	s_and_b64 s[0:1], s[6:7], s[0:1]
	s_mov_b64 exec, s[0:1]
	s_cbranch_execz .LBB0_360
	s_add_i32 s1, 0, 0x23fc0
	v_mov_b32_e32 v0, s1
	s_getreg_b32 s0, hwreg(HW_REG_XCC_ID, 0, 4)
	s_waitcnt vmcnt(0) expcnt(0) lgkmcnt(0)
	ds_read_b32 v2, v0
	s_add_i32 s1, 0, 0x23fc4
	v_mov_b32_e32 v0, s1
	ds_read_b32 v0, v0
	s_and_b32 s0, s0, 15
	s_waitcnt lgkmcnt(1)
	v_cmp_ne_u32_e32 vcc, 0, v2
	s_cbranch_vccnz .LBB0_324
	s_load_dwordx2 s[4:5], s[82:83], 0x100
	s_load_dword s1, s[82:83], 0x108
	s_mov_b32 s3, 1
	v_mov_b32_e32 v16, 0
	s_waitcnt lgkmcnt(0)
	s_mul_i32 s1, s5, s1
	s_mul_i32 s1, s1, s4
	s_add_u32 s4, s8, 0x19a1300
	s_addc_u32 s5, s9, 0
	s_add_u32 s10, s8, 0x19a1500
	s_addc_u32 s11, s9, 0
	s_add_u32 s12, s8, 0x19a1600
	s_addc_u32 s13, s9, 0
	s_add_u32 s14, s8, 0x19a1700
	s_addc_u32 s15, s9, 0
	s_add_u32 s16, s8, 0x19a1800
	s_addc_u32 s17, s9, 0
	s_add_u32 s18, s8, 0x19a1900
	s_addc_u32 s19, s9, 0
	s_add_u32 s20, s8, 0x19a1a00
	s_addc_u32 s21, s9, 0
	s_add_u32 s22, s8, 0x19a1b00
	s_addc_u32 s23, s9, 0
	s_add_u32 s24, s8, 0x19a1c00
	s_addc_u32 s25, s9, 0
	s_add_u32 s26, s8, 0x19a1d00
	s_addc_u32 s27, s9, 0
	s_add_u32 s28, s8, 0x19a1e00
	s_addc_u32 s29, s9, 0
	s_add_u32 s30, s8, 0x19a1f00
	s_addc_u32 s31, s9, 0
	s_add_u32 s34, s8, 0x19a2000
	s_addc_u32 s35, s9, 0
	s_add_u32 s36, s8, 0x19a2100
	s_addc_u32 s37, s9, 0
	s_add_u32 s38, s8, 0x19a2200
	s_addc_u32 s39, s9, 0
	s_add_u32 s40, s8, 0x19a2300
	s_addc_u32 s41, s9, 0
	s_add_u32 s42, s8, 0x19a2400
	s_addc_u32 s43, s9, 0
	s_branch .LBB0_312
